# seam acquire hoist: buffer_inv sc1 issued right after the arrive (overlaps counter round trips) at group seams 1,2,4,5,7,11,12 and chip-wide seams 3,10; seams 8,9 keep it after the wait
# speedup vs baseline: 1.0049x; 1.0028x over previous
.LBB0_400:
	s_or_b64 exec, exec, s[6:7]
	v_mov_b32_e32 v1, 0
	global_load_dword v4, v1, s[2:3] sc1
	buffer_inv sc1
	s_waitcnt vmcnt(1)
	v_readfirstlane_b32 s4, v3
	s_nop 1
	v_add_u32_e32 v2, s4, v2
	v_and_b32_e32 v2, -4, v2
	v_add_u32_e32 v2, 4, v2
	s_waitcnt vmcnt(0)
	v_cmp_lt_u32_e32 vcc, v4, v2
	s_and_saveexec_b64 s[4:5], vcc
	s_cbranch_execz .LBB0_412
	s_add_u32 s6, s82, 0x4200
	s_addc_u32 s7, s83, 0
	s_mov_b32 s18, 1
	s_mov_b64 s[8:9], 0
	s_branch .LBB0_403

.LBB0_412:
	s_or_b64 exec, exec, s[4:5]
	s_waitcnt vmcnt(0)
	s_waitcnt vmcnt(0)

.LBB0_790:
	s_or_b64 exec, exec, s[6:7]
	buffer_inv sc1
	v_cvt_f32_u32_e32 v5, v3
	s_waitcnt vmcnt(1)
	v_readfirstlane_b32 s4, v4
	v_sub_u32_e32 v4, 0, v3
	v_rcp_iflag_f32_e32 v5, v5
	v_add_u32_e32 v6, s4, v2
	v_mul_f32_e32 v5, 0x4f7ffffe, v5
	v_cvt_u32_f32_e32 v5, v5
	v_mul_lo_u32 v2, v4, v5
	v_mul_hi_u32 v2, v5, v2
	v_add_u32_e32 v2, v5, v2
	v_mul_hi_u32 v2, v6, v2
	v_mul_lo_u32 v4, v2, v3
	v_sub_u32_e32 v4, v6, v4
	v_add_u32_e32 v5, 1, v2
	v_cmp_ge_u32_e32 vcc, v4, v3
	s_nop 1
	v_cndmask_b32_e32 v2, v2, v5, vcc
	v_sub_u32_e32 v5, v4, v3
	v_cndmask_b32_e32 v4, v4, v5, vcc
	v_add_u32_e32 v5, 1, v2
	v_cmp_ge_u32_e32 vcc, v4, v3
	v_add_u32_e32 v4, 1, v6
	s_nop 0
	v_cndmask_b32_e32 v2, v2, v5, vcc
	v_mul_lo_u32 v5, v3, v2
	v_add_u32_e32 v3, v5, v3
	v_cmp_ne_u32_e32 vcc, v4, v3
	s_and_saveexec_b64 s[4:5], vcc
	s_xor_b64 s[4:5], exec, s[4:5]
	s_cbranch_execz .LBB0_804
	s_waitcnt lgkmcnt(0)
	v_mov_b32_e32 v1, 0x2000
	global_load_dword v1, v1, s[2:3] offset:1024 sc1
	s_add_u32 s10, s2, 0x2400
	s_addc_u32 s11, s3, 0
	s_waitcnt vmcnt(0)
	v_cmp_eq_u32_e32 vcc, v1, v2
	s_and_saveexec_b64 s[6:7], vcc
	s_cbranch_execz .LBB0_803
	s_add_u32 s8, s82, 0x4200
	s_addc_u32 s9, s83, 0
	s_mov_b32 s22, 1
	s_mov_b64 s[12:13], 0
	v_mov_b32_e32 v1, 0
	s_branch .LBB0_794

.LBB0_803:
	s_or_b64 exec, exec, s[6:7]
	s_waitcnt vmcnt(0)
	s_waitcnt vmcnt(0)

.LBB0_821:
	s_or_b64 exec, exec, s[4:5]
	s_mov_b64 s[4:5], exec
	v_mbcnt_lo_u32_b32 v1, s4, 0
	v_mbcnt_hi_u32_b32 v1, s5, v1
	v_cmp_eq_u32_e32 vcc, 0, v1
	s_waitcnt vmcnt(0)
	s_and_saveexec_b64 s[6:7], vcc
	s_cbranch_execz .LBB0_823
	s_bcnt1_i32_b64 s4, s[4:5]
	v_mov_b32_e32 v1, 0x2000
	v_mov_b32_e32 v2, s4
	global_atomic_add v1, v2, s[2:3] offset:1024

.Lg5_xdone:
	s_waitcnt vmcnt(0)
	s_waitcnt vmcnt(0)
